# comb9 + P0 Wq conversion: the three later per-chunk gain scalars fetched together with the first (no per-chunk load/wait(0) round trip)
# speedup vs baseline: 1.0033x; 1.0033x over previous
; __device__ __forceinline__ unsigned cvt_pk_bf16(float lo, float hi) { unsigned r; asm volatile("v_cvt_pk_bf16_f32 %0, %1, %2" : "=v"(r) : "v"(lo), "v"(hi)); return r; }
; __global__ void __launch_bounds__(NTHR, 2) fwd_megakernel(Args args) {
;     ...
;             for (int r = 0; r < 4; ++r) { const int idx = i0 + r * G * NTHR; if (idx < D * D / 8) { qa[r] = __builtin_nontemporal_load((const f32x4*)(w_q + (size_t)idx * 8)); qb[r] = __builtin_nontemporal_load((const f32x4*)(w_q + (size_t)idx * 8 + 4)); } }
; #pragma unroll
;             for (int r = 0; r < 4; ++r) { const int idx = i0 + r * G * NTHR; if (idx < D * D / 8) { const float gk = g_xa[idx >> 8]; const f32x4 a = qa[r], b = qb[r];
;                 u32x4 w; w.x = cvt_pk_bf16(a[0] * gk, a[1] * gk); w.y = cvt_pk_bf16(a[2] * gk, a[3] * gk); w.z = cvt_pk_bf16(b[0] * gk, b[1] * gk); w.w = cvt_pk_bf16(b[2] * gk, b[3] * gk);
;                 *(u32x4*)(WQN + (size_t)idx * 8) = w; } } }
.LBB0_135:
	s_or_b64 exec, exec, s[26:27]
	v_ashrrev_i32_e32 v40, 8, v32
	v_ashrrev_i32_e32 v41, 31, v40
	v_lshl_add_u64 v[40:41], v[40:41], 2, s[6:7]
	global_load_dword v40, v[40:41], off
	v_ashrrev_i32_e32 v48, 8, v38
	v_min_i32_e32 v48, 0x7ff, v48
	v_max_i32_e32 v48, 0, v48
	v_mov_b32_e32 v49, 0
	v_lshl_add_u64 v[48:49], v[48:49], 2, s[6:7]
	global_load_dword v44, v[48:49], off
	v_ashrrev_i32_e32 v48, 8, v36
	v_min_i32_e32 v48, 0x7ff, v48
	v_max_i32_e32 v48, 0, v48
	v_mov_b32_e32 v49, 0
	v_lshl_add_u64 v[48:49], v[48:49], 2, s[6:7]
	global_load_dword v45, v[48:49], off
	v_ashrrev_i32_e32 v48, 8, v34
	v_min_i32_e32 v48, 0x7ff, v48
	v_max_i32_e32 v48, 0, v48
	v_mov_b32_e32 v49, 0
	v_lshl_add_u64 v[48:49], v[48:49], 2, s[6:7]
	global_load_dword v46, v[48:49], off
	s_waitcnt vmcnt(0)
	v_mul_f32_e32 v28, v40, v28
	v_mul_f32_e32 v29, v40, v29
	v_mul_f32_e32 v41, v40, v24
	v_mul_f32_e32 v27, v40, v27
	v_cvt_pk_bf16_f32 v24, v28, v29
	v_lshl_add_u64 v[28:29], v[32:33], 4, s[60:61]
	v_mul_f32_e32 v30, v40, v30
	v_mul_f32_e32 v31, v40, v31
	v_mul_f32_e32 v42, v40, v25
	v_mul_f32_e32 v43, v40, v26
	v_cvt_pk_bf16_f32 v25, v30, v31
	v_cvt_pk_bf16_f32 v26, v41, v42
	v_cvt_pk_bf16_f32 v27, v43, v27
	global_store_dwordx4 v[28:29], v[24:27], off
	s_and_saveexec_b64 s[26:27], s[4:5]
	s_cbranch_execz .LBB0_138
	v_ashrrev_i32_e32 v24, 8, v38
	v_ashrrev_i32_e32 v25, 31, v24
	v_lshl_add_u64 v[24:25], v[24:25], 2, s[6:7]
	v_mov_b32_e32 v24, v44
	s_nop 0
	v_mul_f32_e32 v25, v24, v12
	v_mul_f32_e32 v26, v24, v13
	v_mul_f32_e32 v28, v24, v15
	v_mul_f32_e32 v29, v24, v0
	v_mul_f32_e32 v27, v24, v14
	v_mul_f32_e32 v30, v24, v1
	v_mul_f32_e32 v31, v24, v2
	v_mul_f32_e32 v33, v24, v3
	v_cvt_pk_bf16_f32 v24, v25, v26
	v_cvt_pk_bf16_f32 v25, v27, v28
	v_cvt_pk_bf16_f32 v26, v29, v30
	v_lshl_add_u64 v[28:29], v[38:39], 4, s[60:61]
	v_cvt_pk_bf16_f32 v27, v31, v33
	global_store_dwordx4 v[28:29], v[24:27], off
	s_or_b64 exec, exec, s[26:27]
	s_and_saveexec_b64 s[4:5], s[2:3]
	s_cbranch_execnz .LBB0_139

; __device__ __forceinline__ unsigned cvt_pk_bf16(float lo, float hi) { unsigned r; asm volatile("v_cvt_pk_bf16_f32 %0, %1, %2" : "=v"(r) : "v"(lo), "v"(hi)); return r; }
; __global__ void __launch_bounds__(NTHR, 2) fwd_megakernel(Args args) {
;     ...
;             for (int r = 0; r < 4; ++r) { const int idx = i0 + r * G * NTHR; if (idx < D * D / 8) { const float gk = g_xa[idx >> 8]; const f32x4 a = qa[r], b = qb[r];
;                 u32x4 w; w.x = cvt_pk_bf16(a[0] * gk, a[1] * gk); w.y = cvt_pk_bf16(a[2] * gk, a[3] * gk); w.z = cvt_pk_bf16(b[0] * gk, b[1] * gk); w.w = cvt_pk_bf16(b[2] * gk, b[3] * gk);
;                 *(u32x4*)(WQN + (size_t)idx * 8) = w; } } }
.LBB0_139:
	v_ashrrev_i32_e32 v24, 8, v36
	v_ashrrev_i32_e32 v25, 31, v24
	v_lshl_add_u64 v[24:25], v[24:25], 2, s[6:7]
	v_mov_b32_e32 v24, v45
	s_nop 0
	v_mul_f32_e32 v25, v24, v16
	v_mul_f32_e32 v26, v24, v17
	v_mul_f32_e32 v28, v24, v19
	v_mul_f32_e32 v29, v24, v4
	v_mul_f32_e32 v27, v24, v18
	v_mul_f32_e32 v30, v24, v5
	v_mul_f32_e32 v31, v24, v6
	v_mul_f32_e32 v33, v24, v7
	v_cvt_pk_bf16_f32 v24, v25, v26
	v_cvt_pk_bf16_f32 v25, v27, v28
	v_cvt_pk_bf16_f32 v26, v29, v30
	v_lshl_add_u64 v[28:29], v[36:37], 4, s[60:61]
	v_cvt_pk_bf16_f32 v27, v31, v33
	global_store_dwordx4 v[28:29], v[24:27], off
	s_or_b64 exec, exec, s[4:5]
	s_and_saveexec_b64 s[2:3], vcc
	s_cbranch_execz .LBB0_128
.LBB0_140:
	v_ashrrev_i32_e32 v24, 8, v34
	v_ashrrev_i32_e32 v25, 31, v24
	v_lshl_add_u64 v[24:25], v[24:25], 2, s[6:7]
	v_mov_b32_e32 v24, v46
	s_nop 0
	v_mul_f32_e32 v25, v24, v20
	v_mul_f32_e32 v26, v24, v21
	v_mul_f32_e32 v28, v24, v23
	v_mul_f32_e32 v29, v24, v8
	v_mul_f32_e32 v27, v24, v22
	v_mul_f32_e32 v30, v24, v9
	v_mul_f32_e32 v31, v24, v10
	v_mul_f32_e32 v33, v24, v11
	v_cvt_pk_bf16_f32 v24, v25, v26
	v_cvt_pk_bf16_f32 v25, v27, v28
	v_cvt_pk_bf16_f32 v26, v29, v30
	v_lshl_add_u64 v[28:29], v[34:35], 4, s[60:61]
	v_cvt_pk_bf16_f32 v27, v31, v33
	global_store_dwordx4 v[28:29], v[24:27], off
	s_branch .LBB0_128
